# v11: + GLA scan gate: log(1+exp(-|x|)) argument is in (1,2] so the denormal scaling / inf select around v_log_f32 and the fmaxf self-canonicalisation are dropped (bit-identical)
# speedup vs baseline: 1.0199x; 1.0022x over previous
; #define LAUNDER(t) const int t = opaque_tid(wv)
; __device__ __forceinline__ void phase_scan(const bf16_t* QK, const bf16_t* V, const float* GLR, bf16_t* OFW, const float* wgate, const float* bgate, char* lds, int wv,
;                                            bf16_t* Z, const float* gn, unsigned long long* X, unsigned tag) {
;     ...
;                     LAUNDER(t); const int ln = t & 63, r32 = ln & 31, hi = ln >> 5, cb = wid >> 2, db = wid & 3, d = db * 32 + r32;
;                     f32x4 ar[4];
; #pragma unroll
;                     for (int i = 0; i < 4; ++i) ar[i] = *(const f32x4*)(lds + OFF_GLR + (cb * 32 + r32) * 64 + i * 16);
;                     asm volatile("s_waitcnt lgkmcnt(0)" ::: "memory"); __builtin_amdgcn_sched_barrier(0);
;                     f32x16 pa;
; #pragma unroll
;                     for (int r = 0; r < 16; ++r) pa[r] = bgv;
; #pragma unroll
;                     for (int kk = 0; kk < 8; ++kk) { const float a = hi ? ar[kk >> 1][2 * (kk & 1) + 1] : ar[kk >> 1][2 * (kk & 1)];
;                         pa = __builtin_amdgcn_mfma_f32_32x32x2f32(a, wgb[kk], pa, 0, 0, 0); }
;                     float lgv[16], pl[16];
; #pragma unroll
;                     for (int r = 0; r < 16; ++r) { const float pre = pa[r]; lgv[r] = -(fmaxf(-pre, 0.f) + __logf(1.f + __expf(-fabsf(pre)))) * (0.0625f * 1.4426950408889634f); }
; #pragma unroll
;                     for (int k = 0; k < 4; ++k) { pl[4 * k] = lgv[4 * k]; pl[4 * k + 1] = pl[4 * k] + lgv[4 * k + 1]; pl[4 * k + 2] = pl[4 * k + 1] + lgv[4 * k + 2]; pl[4 * k + 3] = pl[4 * k + 2] + lgv[4 * k + 3]; }
; #pragma unroll
;                     for (int k = 0; k < 4; ++k) *(float*)(lds + OFF_P + ((cb * 8 + 2 * k + hi) * 128 + d) * 4) = pl[4 * k + 3];
.LBB0_523:
	s_nop 1
	v_mov_b32_e32 v80, v233
	s_nop 0
	v_and_b32_e32 v97, 31, v80
	v_lshl_add_u32 v81, v97, 6, s29
	ds_read_b128 v[98:101], v81
	ds_read_b128 v[102:105], v81 offset:16
	ds_read_b128 v[106:109], v81 offset:32
	ds_read_b128 v[160:163], v81 offset:48
	s_waitcnt lgkmcnt(0)
	v_bfe_u32 v96, v80, 5, 1
	v_and_b32_e32 v80, 32, v80
	v_cmp_ne_u32_e64 s[6:7], 0, v80
	v_cmp_eq_u32_e32 vcc, 0, v96
	s_waitcnt lgkmcnt(3)
	v_cndmask_b32_e64 v110, v98, v99, s[6:7]
	s_nop 1
	v_mfma_f32_32x32x2_f32 v[80:95], v110, v243, v[0:15]
	v_cndmask_b32_e64 v110, 3, 2, vcc
	v_cmp_eq_u32_e64 s[8:9], 1, v110
	s_nop 1
	v_cndmask_b32_e64 v98, v98, v99, s[8:9]
	v_cndmask_b32_e32 v98, v98, v100, vcc
	v_cndmask_b32_e64 v98, v98, v101, s[6:7]
	s_nop 1
	v_mfma_f32_32x32x2_f32 v[80:95], v98, v237, v[80:95]
	s_waitcnt lgkmcnt(2)
	v_cndmask_b32_e64 v98, v102, v103, s[6:7]
	s_nop 1
	v_mfma_f32_32x32x2_f32 v[80:95], v98, v238, v[80:95]
	v_cndmask_b32_e64 v98, v102, v103, s[8:9]
	v_cndmask_b32_e32 v98, v98, v104, vcc
	v_cndmask_b32_e64 v98, v98, v105, s[6:7]
	s_nop 1
	v_mfma_f32_32x32x2_f32 v[80:95], v98, v239, v[80:95]
	s_waitcnt lgkmcnt(1)
	v_cndmask_b32_e64 v98, v106, v107, s[6:7]
	s_nop 1
	v_mfma_f32_32x32x2_f32 v[80:95], v98, v240, v[80:95]
	v_cndmask_b32_e64 v98, v106, v107, s[8:9]
	v_cndmask_b32_e32 v98, v98, v108, vcc
	v_cndmask_b32_e64 v98, v98, v109, s[6:7]
	s_nop 1
	v_mfma_f32_32x32x2_f32 v[80:95], v98, v241, v[80:95]
	s_waitcnt lgkmcnt(0)
	v_cndmask_b32_e64 v98, v160, v161, s[6:7]
	s_nop 1
	v_mfma_f32_32x32x2_f32 v[80:95], v98, v242, v[80:95]
	v_cndmask_b32_e64 v98, v160, v161, s[8:9]
	v_cndmask_b32_e32 v98, v98, v162, vcc
	v_cndmask_b32_e64 v98, v98, v163, s[6:7]
	s_nop 1
	v_mfma_f32_32x32x2_f32 v[80:95], v98, v244, v[80:95]
	s_nop 15
	s_nop 1
	v_max_f32_e64 v98, -v80, 0
	v_mul_f32_e64 v80, |v80|, s0
	v_exp_f32_e32 v80, v80
	s_nop 0
	v_add_f32_e32 v80, 1.0, v80
	v_log_f32_e32 v80, v80
	s_nop 0
	v_mul_f32_e32 v99, 0x3f317217, v80
	v_fma_f32 v99, v80, s95, -v99
	v_fmac_f32_e32 v99, 0x3377d1cf, v80
	v_fmac_f32_e32 v99, 0x3f317217, v80
	v_mov_b32_e32 v80, v99
	v_add_f32_e32 v80, v98, v80
	v_max_f32_e64 v98, -v81, 0
	v_mul_f32_e64 v81, |v81|, s0
	v_exp_f32_e32 v81, v81
	s_nop 0
	v_add_f32_e32 v81, 1.0, v81
	v_log_f32_e32 v81, v81
	s_nop 0
	v_mul_f32_e32 v99, 0x3f317217, v81
	v_fma_f32 v99, v81, s95, -v99
	v_fmac_f32_e32 v99, 0x3377d1cf, v81
	v_fmac_f32_e32 v99, 0x3f317217, v81
	v_mov_b32_e32 v81, v99
	v_max_f32_e64 v99, -v82, 0
	v_mul_f32_e64 v82, |v82|, s0
	v_exp_f32_e32 v82, v82
	v_add_f32_e32 v81, v98, v81
	v_mul_f32_e32 v98, 0xbdb8aa3b, v81
	v_add_f32_e32 v82, 1.0, v82
	v_fmac_f32_e32 v98, 0xbdb8aa3b, v80
	s_nop 0
	v_log_f32_e32 v82, v82
	s_nop 0
	v_mul_f32_e32 v100, 0x3f317217, v82
	v_fma_f32 v100, v82, s95, -v100
	v_fmac_f32_e32 v100, 0x3377d1cf, v82
	v_fmac_f32_e32 v100, 0x3f317217, v82
	v_mov_b32_e32 v82, v100
	v_add_f32_e32 v82, v99, v82
	v_max_f32_e64 v99, -v83, 0
	v_mul_f32_e64 v83, |v83|, s0
	v_exp_f32_e32 v83, v83
	v_fmamk_f32 v168, v82, 0xbdb8aa3b, v98
	v_add_f32_e32 v83, 1.0, v83
	v_log_f32_e32 v83, v83
	s_nop 0
	v_mul_f32_e32 v100, 0x3f317217, v83
	v_fma_f32 v100, v83, s95, -v100
	v_fmac_f32_e32 v100, 0x3377d1cf, v83
	v_fmac_f32_e32 v100, 0x3f317217, v83
	v_mov_b32_e32 v83, v100
	v_add_f32_e32 v83, v99, v83
	v_max_f32_e64 v99, -v84, 0
	v_mul_f32_e64 v84, |v84|, s0
	v_exp_f32_e32 v84, v84
	v_fmamk_f32 v169, v83, 0xbdb8aa3b, v168
	v_add_f32_e32 v84, 1.0, v84
	v_log_f32_e32 v84, v84
	s_nop 0
	v_mul_f32_e32 v100, 0x3f317217, v84
	v_fma_f32 v100, v84, s95, -v100
	v_fmac_f32_e32 v100, 0x3377d1cf, v84
	v_fmac_f32_e32 v100, 0x3f317217, v84
	v_mov_b32_e32 v84, v100
	v_add_f32_e32 v84, v99, v84
	v_max_f32_e64 v99, -v85, 0
	v_mul_f32_e64 v85, |v85|, s0
	v_exp_f32_e32 v85, v85
	s_nop 0
	v_add_f32_e32 v85, 1.0, v85
	v_log_f32_e32 v85, v85
	s_nop 0
	v_mul_f32_e32 v100, 0x3f317217, v85
	v_fma_f32 v100, v85, s95, -v100
	v_fmac_f32_e32 v100, 0x3377d1cf, v85
	v_fmac_f32_e32 v100, 0x3f317217, v85
	v_mov_b32_e32 v85, v100
	v_max_f32_e64 v100, -v86, 0
	v_mul_f32_e64 v86, |v86|, s0
	v_exp_f32_e32 v86, v86
	v_add_f32_e32 v85, v99, v85
	v_mul_f32_e32 v99, 0xbdb8aa3b, v85
	v_add_f32_e32 v86, 1.0, v86
	v_fmac_f32_e32 v99, 0xbdb8aa3b, v84
	s_nop 0
	v_log_f32_e32 v86, v86
	s_nop 0
	v_mul_f32_e32 v101, 0x3f317217, v86
	v_fma_f32 v101, v86, s95, -v101
	v_fmac_f32_e32 v101, 0x3377d1cf, v86
	v_fmac_f32_e32 v101, 0x3f317217, v86
	v_mov_b32_e32 v86, v101
	v_add_f32_e32 v86, v100, v86
	v_max_f32_e64 v100, -v87, 0
	v_mul_f32_e64 v87, |v87|, s0
	v_exp_f32_e32 v87, v87
	v_fmamk_f32 v170, v86, 0xbdb8aa3b, v99
	v_add_f32_e32 v87, 1.0, v87
	v_log_f32_e32 v87, v87
	s_nop 0
	v_mul_f32_e32 v101, 0x3f317217, v87
	v_fma_f32 v101, v87, s95, -v101
	v_fmac_f32_e32 v101, 0x3377d1cf, v87
	v_fmac_f32_e32 v101, 0x3f317217, v87
	v_mov_b32_e32 v87, v101
	v_add_f32_e32 v87, v100, v87
	v_max_f32_e64 v100, -v88, 0
	v_mul_f32_e64 v88, |v88|, s0
	v_exp_f32_e32 v88, v88
	v_fmamk_f32 v171, v87, 0xbdb8aa3b, v170
	v_add_f32_e32 v88, 1.0, v88
	v_log_f32_e32 v88, v88
	s_nop 0
	v_mul_f32_e32 v101, 0x3f317217, v88
	v_fma_f32 v101, v88, s95, -v101
	v_fmac_f32_e32 v101, 0x3377d1cf, v88
	v_fmac_f32_e32 v101, 0x3f317217, v88
	v_mov_b32_e32 v88, v101
	v_add_f32_e32 v88, v100, v88
	v_max_f32_e64 v100, -v89, 0
	v_mul_f32_e64 v89, |v89|, s0
	v_exp_f32_e32 v89, v89
	s_nop 0
	v_add_f32_e32 v89, 1.0, v89
	v_log_f32_e32 v89, v89
	s_nop 0
	v_mul_f32_e32 v101, 0x3f317217, v89
	v_fma_f32 v101, v89, s95, -v101
	v_fmac_f32_e32 v101, 0x3377d1cf, v89
	v_fmac_f32_e32 v101, 0x3f317217, v89
	v_mov_b32_e32 v89, v101
	v_max_f32_e64 v101, -v90, 0
	v_mul_f32_e64 v90, |v90|, s0
	v_exp_f32_e32 v90, v90
	v_add_f32_e32 v89, v100, v89
; #define LBAR() do { asm volatile("s_waitcnt lgkmcnt(0)" ::: "memory"); __builtin_amdgcn_s_barrier(); asm volatile("" ::: "memory"); } while (0)
; __device__ __forceinline__ void phase_scan(const bf16_t* QK, const bf16_t* V, const float* GLR, bf16_t* OFW, const float* wgate, const float* bgate, char* lds, int wv,
;                                            bf16_t* Z, const float* gn, unsigned long long* X, unsigned tag) {
;     ...
;                     for (int r = 0; r < 16; ++r) { const float pre = pa[r]; lgv[r] = -(fmaxf(-pre, 0.f) + __logf(1.f + __expf(-fabsf(pre)))) * (0.0625f * 1.4426950408889634f); }
; #pragma unroll
;                     for (int k = 0; k < 4; ++k) { pl[4 * k] = lgv[4 * k]; pl[4 * k + 1] = pl[4 * k] + lgv[4 * k + 1]; pl[4 * k + 2] = pl[4 * k + 1] + lgv[4 * k + 2]; pl[4 * k + 3] = pl[4 * k + 2] + lgv[4 * k + 3]; }
; #pragma unroll
;                     for (int k = 0; k < 4; ++k) *(float*)(lds + OFF_P + ((cb * 8 + 2 * k + hi) * 128 + d) * 4) = pl[4 * k + 3];
;                     LBAR();
	v_mul_f32_e32 v100, 0xbdb8aa3b, v89
	v_add_f32_e32 v90, 1.0, v90
	v_fmac_f32_e32 v100, 0xbdb8aa3b, v88
	s_nop 0
	v_log_f32_e32 v90, v90
	s_nop 0
	v_mul_f32_e32 v102, 0x3f317217, v90
	v_fma_f32 v102, v90, s95, -v102
	v_fmac_f32_e32 v102, 0x3377d1cf, v90
	v_fmac_f32_e32 v102, 0x3f317217, v90
	v_mov_b32_e32 v90, v102
	v_add_f32_e32 v101, v101, v90
	v_max_f32_e64 v90, -v91, 0
	v_mul_f32_e64 v91, |v91|, s0
	v_exp_f32_e32 v91, v91
	v_fmamk_f32 v172, v101, 0xbdb8aa3b, v100
	v_add_f32_e32 v91, 1.0, v91
	v_log_f32_e32 v91, v91
	s_nop 0
	v_mul_f32_e32 v102, 0x3f317217, v91
	v_fma_f32 v102, v91, s95, -v102
	v_fmac_f32_e32 v102, 0x3377d1cf, v91
	v_fmac_f32_e32 v102, 0x3f317217, v91
	v_mov_b32_e32 v91, v102
	v_add_f32_e32 v162, v90, v91
	v_mul_f32_e64 v91, |v92|, s0
	v_exp_f32_e32 v91, v91
	v_max_f32_e64 v90, -v92, 0
	v_fmamk_f32 v173, v162, 0xbdb8aa3b, v172
	v_add_f32_e32 v91, 1.0, v91
	v_log_f32_e32 v91, v91
	s_nop 0
	v_mul_f32_e32 v92, 0x3f317217, v91
	v_fma_f32 v92, v91, s95, -v92
	v_fmac_f32_e32 v92, 0x3377d1cf, v91
	v_fmac_f32_e32 v92, 0x3f317217, v91
	v_mov_b32_e32 v91, v92
	v_add_f32_e32 v163, v90, v91
	v_mul_f32_e64 v91, |v93|, s0
	v_exp_f32_e32 v91, v91
	v_max_f32_e64 v90, -v93, 0
	v_add_f32_e32 v91, 1.0, v91
	v_log_f32_e32 v91, v91
	s_nop 0
	v_mul_f32_e32 v92, 0x3f317217, v91
	v_fma_f32 v92, v91, s95, -v92
	v_fmac_f32_e32 v92, 0x3377d1cf, v91
	v_fmac_f32_e32 v92, 0x3f317217, v91
	v_mov_b32_e32 v91, v92
	v_add_f32_e32 v164, v90, v91
	v_mul_f32_e64 v91, |v94|, s0
	v_exp_f32_e32 v91, v91
	v_max_f32_e64 v90, -v94, 0
	v_mul_f32_e32 v165, 0xbdb8aa3b, v164
	v_add_f32_e32 v91, 1.0, v91
	v_fmac_f32_e32 v165, 0xbdb8aa3b, v163
	s_nop 0
	v_log_f32_e32 v91, v91
	s_nop 0
	v_mul_f32_e32 v92, 0x3f317217, v91
	v_fma_f32 v92, v91, s95, -v92
	v_fmac_f32_e32 v92, 0x3377d1cf, v91
	v_fmac_f32_e32 v92, 0x3f317217, v91
	v_mov_b32_e32 v91, v92
	v_add_f32_e32 v166, v90, v91
	v_mul_f32_e64 v91, |v95|, s0
	v_exp_f32_e32 v91, v91
	v_max_f32_e64 v90, -v95, 0
	v_fmamk_f32 v174, v166, 0xbdb8aa3b, v165
	v_add_f32_e32 v91, 1.0, v91
	v_log_f32_e32 v91, v91
	s_nop 0
	v_mul_f32_e32 v92, 0x3f317217, v91
	v_fma_f32 v92, v91, s95, -v92
	v_fmac_f32_e32 v92, 0x3377d1cf, v91
	v_fmac_f32_e32 v92, 0x3f317217, v91
	v_mov_b32_e32 v91, v92
	v_add_f32_e32 v167, v90, v91
	v_or_b32_e32 v90, s53, v97
	v_lshlrev_b32_e32 v97, 2, v90
	v_add_u32_e32 v90, 0, v97
	v_lshlrev_b32_e32 v91, 9, v96
	v_add3_u32 v91, v90, s27, v91
	v_fmamk_f32 v175, v167, 0xbdb8aa3b, v174
	ds_write2st64_b32 v91, v169, v171 offset0:148 offset1:152
	ds_write2st64_b32 v91, v173, v175 offset0:156 offset1:160
	s_waitcnt lgkmcnt(0)
	s_barrier
; __device__ __forceinline__ void phase_scan(const bf16_t* QK, const bf16_t* V, const float* GLR, bf16_t* OFW, const float* wgate, const float* bgate, char* lds, int wv,
;                                            bf16_t* Z, const float* gn, unsigned long long* X, unsigned tag) {
;     ...
;                     float gsv[16];
; #pragma unroll
;                     for (int g = 0; g < 16; ++g) gsv[g] = *(const float*)(lds + OFF_P + (g * 128 + d) * 4);
;                     asm volatile("s_waitcnt lgkmcnt(0)" ::: "memory"); __builtin_amdgcn_sched_barrier(0);
;                     float ex[16]; float run = 0.f;
; #pragma unroll
;                     for (int g = 0; g < 16; ++g) { ex[g] = run; run += gsv[g]; }
;                     const float tot = run;
; #pragma unroll
;                     for (int k = 0; k < 4; ++k) { const float e0 = cb ? ex[8 + 2 * k] : ex[2 * k], e1 = cb ? ex[8 + 2 * k + 1] : ex[2 * k + 1]; const float off = hi ? e1 : e0;
; #pragma unroll
;                         for (int e = 0; e < 4; ++e) { const int r = 4 * k + e; const float bc = dir == 0 ? off + pl[r] : tot - (off + pl[r] - lgv[r]);
;                             *(float*)(lds + OFF_BC + (cb * 32 + e + 8 * k + 4 * hi) * BC_ST + d * 4) = bc; } }
;                     if (cb == 0 && hi == 0) *(float*)(lds + OFF_EBT + d * 4) = __builtin_amdgcn_exp2f(tot);
	ds_read2st64_b32 v[92:93], v90 offset0:148 offset1:150
	ds_read2st64_b32 v[94:95], v90 offset0:152 offset1:154
	ds_read2st64_b32 v[102:103], v90 offset0:156 offset1:158
	ds_read2st64_b32 v[104:105], v90 offset0:160 offset1:162
	ds_read2st64_b32 v[106:107], v90 offset0:164 offset1:166
	ds_read2st64_b32 v[108:109], v90 offset0:168 offset1:170
	ds_read2st64_b32 v[110:111], v90 offset0:172 offset1:174
	ds_read2st64_b32 v[160:161], v90 offset0:176 offset1:178
	s_waitcnt lgkmcnt(0)
	s_waitcnt lgkmcnt(7)
	v_add_f32_e32 v92, 0, v92
	v_add_f32_e32 v93, v92, v93
	s_waitcnt lgkmcnt(6)
	v_add_f32_e32 v94, v93, v94
	v_add_f32_e32 v95, v94, v95
	s_waitcnt lgkmcnt(5)
	v_add_f32_e32 v102, v95, v102
	v_add_f32_e32 v103, v102, v103
	s_waitcnt lgkmcnt(4)
	v_add_f32_e32 v104, v103, v104
	v_add_f32_e32 v105, v104, v105
	s_waitcnt lgkmcnt(3)
	v_add_f32_e32 v106, v105, v106
	v_add_f32_e32 v107, v106, v107
	s_waitcnt lgkmcnt(2)
	v_add_f32_e32 v108, v107, v108
	v_add_f32_e32 v109, v108, v109
	s_waitcnt lgkmcnt(1)
	v_add_f32_e32 v110, v109, v110
	v_lshl_or_b32 v96, v96, 2, s40
	v_cndmask_b32_e64 v105, v105, 0, s[4:5]
	v_cndmask_b32_e64 v92, v106, v92, s[4:5]
	v_add_f32_e32 v111, v110, v111
	s_add_i32 s8, 0, 0x14800
	v_cndmask_b32_e32 v92, v92, v105, vcc
	v_mul_lo_u32 v96, v96, s91
	s_waitcnt lgkmcnt(0)
	v_add_f32_e32 v160, v111, v160
	v_fmamk_f32 v105, v80, 0xbdb8aa3b, v92
	v_add3_u32 v96, s8, v97, v96
	v_add_f32_e32 v97, v98, v92
	v_add_f32_e32 v91, v160, v161
	v_fmamk_f32 v80, v80, 0x3db8aa3b, v105
	v_fmamk_f32 v81, v81, 0x3db8aa3b, v97
	v_sub_f32_e32 v80, v91, v80
	v_sub_f32_e32 v81, v91, v81
	v_cndmask_b32_e64 v80, v80, v105, s[60:61]
	v_cndmask_b32_e64 v81, v81, v97, s[60:61]
	ds_write2_b32 v96, v80, v81 offset1:132
	v_add_f32_e32 v80, v168, v92
	v_fmamk_f32 v81, v82, 0x3db8aa3b, v80
	v_sub_f32_e32 v81, v91, v81
	v_cndmask_b32_e64 v80, v81, v80, s[60:61]
	v_add_f32_e32 v81, v169, v92
	v_fmamk_f32 v82, v83, 0x3db8aa3b, v81
	v_sub_f32_e32 v82, v91, v82
	v_cndmask_b32_e64 v81, v82, v81, s[60:61]
	v_add_u32_e32 v82, 0x400, v96
	ds_write2_b32 v82, v80, v81 offset0:8 offset1:140
	v_cndmask_b32_e64 v80, v107, v93, s[4:5]
	v_cndmask_b32_e64 v81, v108, v94, s[4:5]
	v_cndmask_b32_e32 v80, v81, v80, vcc
	v_fmamk_f32 v81, v84, 0xbdb8aa3b, v80
	v_fmamk_f32 v82, v84, 0x3db8aa3b, v81
	v_sub_f32_e32 v82, v91, v82
	v_cndmask_b32_e64 v81, v82, v81, s[60:61]
	v_add_f32_e32 v82, v99, v80
	v_fmamk_f32 v83, v85, 0x3db8aa3b, v82
	v_sub_f32_e32 v83, v91, v83
	v_cndmask_b32_e64 v82, v83, v82, s[60:61]
	v_add_u32_e32 v83, 0x1000, v96
	ds_write2_b32 v83, v81, v82 offset0:32 offset1:164
	v_add_f32_e32 v81, v170, v80
	v_fmamk_f32 v82, v86, 0x3db8aa3b, v81
	v_sub_f32_e32 v82, v91, v82
	v_add_f32_e32 v80, v171, v80
	v_cndmask_b32_e64 v81, v82, v81, s[60:61]
	v_fmamk_f32 v82, v87, 0x3db8aa3b, v80
	v_sub_f32_e32 v82, v91, v82
	v_cndmask_b32_e64 v80, v82, v80, s[60:61]
	v_add_u32_e32 v82, 0x1400, v96
	ds_write2_b32 v82, v81, v80 offset0:40 offset1:172
	v_cndmask_b32_e64 v80, v109, v95, s[4:5]
	v_cndmask_b32_e64 v81, v110, v102, s[4:5]
	v_cndmask_b32_e32 v80, v81, v80, vcc
	v_fmamk_f32 v81, v88, 0xbdb8aa3b, v80
	v_fmamk_f32 v82, v88, 0x3db8aa3b, v81
	v_sub_f32_e32 v82, v91, v82
	v_cndmask_b32_e64 v81, v82, v81, s[60:61]
	v_add_f32_e32 v82, v100, v80
	v_fmamk_f32 v83, v89, 0x3db8aa3b, v82
	v_sub_f32_e32 v83, v91, v83
	v_cndmask_b32_e64 v82, v83, v82, s[60:61]
	v_add_u32_e32 v83, 0x2000, v96
	ds_write2_b32 v83, v81, v82 offset0:64 offset1:196
	v_add_f32_e32 v81, v172, v80
	v_fmamk_f32 v82, v101, 0x3db8aa3b, v81
	v_sub_f32_e32 v82, v91, v82
	v_add_f32_e32 v80, v173, v80
	v_cndmask_b32_e64 v81, v82, v81, s[60:61]
	v_fmamk_f32 v82, v162, 0x3db8aa3b, v80
	v_sub_f32_e32 v82, v91, v82
	v_cndmask_b32_e64 v80, v82, v80, s[60:61]
	v_add_u32_e32 v82, 0x2400, v96
	ds_write2_b32 v82, v81, v80 offset0:72 offset1:204
	v_cndmask_b32_e64 v80, v111, v103, s[4:5]
	v_cndmask_b32_e64 v81, v160, v104, s[4:5]
	v_cndmask_b32_e32 v80, v81, v80, vcc
	v_fmamk_f32 v81, v163, 0xbdb8aa3b, v80
	v_fmamk_f32 v82, v163, 0x3db8aa3b, v81
	v_sub_f32_e32 v82, v91, v82
	v_cndmask_b32_e64 v81, v82, v81, s[60:61]
	v_add_f32_e32 v82, v165, v80
	v_fmamk_f32 v83, v164, 0x3db8aa3b, v82
	v_sub_f32_e32 v83, v91, v83
	v_cndmask_b32_e64 v82, v83, v82, s[60:61]
	v_add_u32_e32 v83, 0x3000, v96
	ds_write2_b32 v83, v81, v82 offset0:96 offset1:228
	v_add_f32_e32 v81, v174, v80
	v_fmamk_f32 v82, v166, 0x3db8aa3b, v81
	v_sub_f32_e32 v82, v91, v82
	v_add_f32_e32 v80, v175, v80
	v_cndmask_b32_e64 v81, v82, v81, s[60:61]
	v_fmamk_f32 v82, v167, 0x3db8aa3b, v80
	v_sub_f32_e32 v82, v91, v82
	v_cndmask_b32_e64 v80, v82, v80, s[60:61]
	v_add_u32_e32 v82, 0x3400, v96
	s_and_b64 s[34:35], s[4:5], vcc
	ds_write2_b32 v82, v81, v80 offset0:104 offset1:236
	s_and_saveexec_b64 s[6:7], s[34:35]
	s_cbranch_execz .LBB0_525
	v_exp_f32_e32 v80, v91
	v_add_u32_e32 v81, 0x1e400, v90
	ds_write_b32 v81, v80
